# grid barrier: per-CU L1 invalidate (buffer_inv sc1) issued at barrier entry instead of after the flag (CU idle in between, polls are sc1)
# speedup vs baseline: 1.0117x; 1.0117x over previous
.LBB0_113:
	s_load_dwordx2 s[2:3], s[0:1], 0xf0
	s_waitcnt vmcnt(0)
	s_waitcnt lgkmcnt(0)
	s_barrier
	v_writelane_b32 v242, s2, 4
	s_nop 1
	v_writelane_b32 v242, s3, 5
	s_and_saveexec_b64 s[2:3], s[94:95]
	s_load_dwordx2 s[38:39], s[0:1], 0x4c8
	s_cbranch_execz .LBB0_165
	v_mov_b32_e32 v0, 0x26000
	s_waitcnt vmcnt(0) expcnt(0) lgkmcnt(0)
	buffer_inv sc1
	ds_read_b32 v2, v0
	v_mov_b32_e32 v0, 0x26004
	ds_read_b32 v0, v0
	s_waitcnt lgkmcnt(1)
	v_cmp_ne_u32_e32 vcc, 0, v2
	s_cbranch_vccnz .LBB0_129
	s_load_dwordx2 s[12:13], s[0:1], 0xf8
	s_mul_i32 s20, s39, s33
	s_mul_i32 s20, s20, s38
	s_mov_b32 s21, 1
	v_mov_b32_e32 v16, 0
	s_waitcnt lgkmcnt(0)
	s_add_u32 s6, s12, 0x1000
	s_addc_u32 s7, s13, 0
	s_add_u32 s8, s12, 0x1100
	s_addc_u32 s9, s13, 0
	s_add_u32 s10, s12, 0x1200
	s_addc_u32 s11, s13, 0
	s_add_u32 s12, s12, 0x1300
	s_addc_u32 s13, s13, 0
	s_branch .LBB0_117

.LBB0_144:
	s_or_b64 exec, exec, s[10:11]
	s_waitcnt vmcnt(0)
	s_waitcnt vmcnt(0)

.LBB0_162:
	s_or_b64 exec, exec, s[8:9]
	s_mov_b64 s[8:9], exec
	v_mbcnt_lo_u32_b32 v0, s8, 0
	v_mbcnt_hi_u32_b32 v0, s9, v0
	v_cmp_eq_u32_e32 vcc, 0, v0
	s_waitcnt vmcnt(0)
	s_and_saveexec_b64 s[10:11], vcc
	s_cbranch_execz .LBB0_164
	s_bcnt1_i32_b64 s8, s[8:9]
	v_mov_b32_e32 v0, 0x2000
	v_mov_b32_e32 v1, s8
	global_atomic_add v0, v1, s[6:7] offset:1024

.LBB0_214:
	s_waitcnt vmcnt(0)
	s_barrier
	s_and_saveexec_b64 s[2:3], s[4:5]
	s_xor_b64 s[2:3], exec, s[2:3]
	s_lshl_b32 s6, s60, 6
	s_mov_b32 s7, 0
	s_or_saveexec_b64 s[2:3], s[2:3]
	v_mov_b64_e32 v[0:1], s[6:7]
	s_xor_b64 exec, exec, s[2:3]
	s_cbranch_execz .LBB0_269
	v_mov_b32_e32 v0, 0x26000
	s_waitcnt vmcnt(0) expcnt(0) lgkmcnt(0)
	buffer_inv sc1
	ds_read_b32 v2, v0
	v_mov_b32_e32 v0, 0x26004
	ds_read_b32 v0, v0
	s_waitcnt lgkmcnt(1)
	v_cmp_ne_u32_e32 vcc, 0, v2
	s_cbranch_vccnz .LBB0_232
	s_load_dwordx2 s[10:11], s[0:1], 0xf8
	s_mul_i32 s18, s39, s33
	s_mul_i32 s18, s18, s38
	s_mov_b32 s19, 1
	v_mov_b32_e32 v16, 0
	s_waitcnt lgkmcnt(0)
	s_add_u32 s4, s10, 0x1000
	s_addc_u32 s5, s11, 0
	s_add_u32 s6, s10, 0x1100
	s_addc_u32 s7, s11, 0
	s_add_u32 s8, s10, 0x1200
	s_addc_u32 s9, s11, 0
	s_add_u32 s10, s10, 0x1300
	s_addc_u32 s11, s11, 0
	s_branch .LBB0_220

.LBB0_265:
	s_or_b64 exec, exec, s[10:11]
	s_mov_b64 s[10:11], exec
	v_mbcnt_lo_u32_b32 v0, s10, 0
	v_mbcnt_hi_u32_b32 v0, s11, v0
	v_cmp_eq_u32_e32 vcc, 0, v0
	s_waitcnt vmcnt(0)
	s_and_saveexec_b64 s[12:13], vcc
	s_cbranch_execz .LBB0_267
	s_bcnt1_i32_b64 s10, s[10:11]
	v_mov_b32_e32 v0, 0x2000
	v_mov_b32_e32 v1, s10
	global_atomic_add v0, v1, s[6:7] offset:1024

.LBB0_270:
	s_or_b64 exec, exec, s[2:3]
	s_waitcnt vmcnt(0)
	global_atomic_add v[142:143], v166, off
	s_waitcnt vmcnt(0)

.LBB0_395:
	s_waitcnt vmcnt(0)
	s_waitcnt vmcnt(63) expcnt(7) lgkmcnt(15)
	s_barrier
	s_and_saveexec_b64 s[0:1], s[94:95]
	s_cbranch_execz .LBB0_443
	s_waitcnt vmcnt(0) expcnt(0) lgkmcnt(0)
	buffer_inv sc1
	ds_read_b32 v2, v164
	ds_read_b32 v0, v165
	s_waitcnt lgkmcnt(1)
	v_cmp_ne_u32_e32 vcc, 0, v2
	s_cbranch_vccnz .LBB0_411
	s_mov_b32 s8, 1
	s_branch .LBB0_399

.LBB0_424:
	s_or_b64 exec, exec, s[4:5]
	s_waitcnt vmcnt(0)
	s_waitcnt vmcnt(0)

.LBB0_519:
	s_waitcnt vmcnt(0)
	s_barrier
	s_and_saveexec_b64 s[0:1], s[94:95]
	s_cbranch_execz .LBB0_567
	s_waitcnt vmcnt(0) expcnt(0) lgkmcnt(0)
	buffer_inv sc1
	ds_read_b32 v2, v164
	ds_read_b32 v0, v165
	s_waitcnt lgkmcnt(1)
	v_cmp_ne_u32_e32 vcc, 0, v2
	s_cbranch_vccnz .LBB0_535
	s_mov_b32 s8, 1
	s_branch .LBB0_523

.LBB0_777:
	s_waitcnt vmcnt(0)
	s_barrier
	s_and_saveexec_b64 s[0:1], s[94:95]
	s_mov_b64 s[16:17], 0x6fb4080
	s_mov_b64 s[20:21], 0x6fd4080
	v_readlane_b32 s22, v241, 41
	v_readlane_b32 s23, v241, 42
	s_cbranch_execz .LBB0_825
	s_waitcnt vmcnt(0) expcnt(0) lgkmcnt(0)
	buffer_inv sc1
	ds_read_b32 v2, v164
	ds_read_b32 v0, v165
	s_waitcnt lgkmcnt(1)
	v_cmp_ne_u32_e32 vcc, 0, v2
	s_cbranch_vccnz .LBB0_793
	s_mov_b32 s8, 1
	s_branch .LBB0_781

.LBB0_1319:
	s_waitcnt vmcnt(0)
	s_barrier
	s_and_saveexec_b64 s[0:1], s[94:95]
	v_readlane_b32 s26, v241, 43
	s_mov_b64 s[16:17], 0x6fb4080
	s_mov_b64 s[20:21], 0x6fd4080
	v_readlane_b32 s22, v241, 41
	v_readlane_b32 s27, v241, 44
	v_readlane_b32 s23, v241, 42
	s_cbranch_execz .LBB0_1367
	s_waitcnt vmcnt(0) expcnt(0) lgkmcnt(0)
	buffer_inv sc1
	ds_read_b32 v2, v164
	ds_read_b32 v0, v165
	s_waitcnt lgkmcnt(1)
	v_cmp_ne_u32_e32 vcc, 0, v2
	s_cbranch_vccnz .LBB0_1335
	s_mov_b32 s8, 1
	s_branch .LBB0_1323

.LBB0_1377:
	s_waitcnt vmcnt(0)
	s_barrier
	s_and_saveexec_b64 s[2:3], s[94:95]
	s_mov_b64 s[16:17], 0x80000
	s_mov_b64 s[20:21], 0x100000
	s_cbranch_execz .LBB0_1425
	s_waitcnt vmcnt(0) expcnt(0) lgkmcnt(0)
	buffer_inv sc1
	ds_read_b32 v2, v164
	ds_read_b32 v0, v165
	s_waitcnt lgkmcnt(1)
	v_cmp_ne_u32_e32 vcc, 0, v2
	s_cbranch_vccnz .LBB0_1393
	s_mov_b32 s1, 1
	s_branch .LBB0_1381

.LBB0_1406:
	s_or_b64 exec, exec, s[6:7]
	s_waitcnt vmcnt(0)
	s_waitcnt vmcnt(0)

.LBB0_1424:
	s_or_b64 exec, exec, s[4:5]
	s_waitcnt vmcnt(0)
	global_atomic_add v[142:143], v166, off
	s_waitcnt vmcnt(0)

.LBB0_1530:
	v_readlane_b32 s22, v241, 41
	s_and_b64 vcc, exec, s[42:43]
	s_mov_b64 s[16:17], 0x6fb4080
	s_mov_b64 s[20:21], 0x6fd4080
	v_readlane_b32 s23, v241, 42
	s_cbranch_vccz .LBB0_272
	s_waitcnt vmcnt(0)
	s_barrier
	s_and_saveexec_b64 s[0:1], s[94:95]
	s_cbranch_execz .LBB0_271
	s_waitcnt vmcnt(0) expcnt(0) lgkmcnt(0)
	buffer_inv sc1
	ds_read_b32 v2, v164
	ds_read_b32 v0, v165
	s_waitcnt lgkmcnt(1)
	v_cmp_ne_u32_e32 vcc, 0, v2
	s_cbranch_vccnz .LBB0_1547
	s_mov_b32 s8, 1
	s_branch .LBB0_1535
